# k33: k20 + cooperative-groups grid.sync after phase 0 replaced by the workspace counter barrier (btarget starts at gridDim)
# speedup vs baseline: 1.0022x; 1.0022x over previous
; __device__ __forceinline__ void gbar(unsigned* ctr, unsigned& target) {
;     asm volatile("s_waitcnt vmcnt(0) lgkmcnt(0)" ::: "memory");
;     __syncthreads();
;     target += gridDim.x;
;     if (threadIdx.x == 0) {
;         __builtin_amdgcn_fence(__ATOMIC_RELEASE, "agent");
;         asm volatile("s_waitcnt vmcnt(0)" ::: "memory");
;         __hip_atomic_fetch_add(ctr, 1u, __ATOMIC_RELAXED, __HIP_MEMORY_SCOPE_AGENT);
;         while (__hip_atomic_load(ctr, __ATOMIC_RELAXED, __HIP_MEMORY_SCOPE_AGENT) < target) __builtin_amdgcn_s_sleep(2);
;         __builtin_amdgcn_fence(__ATOMIC_ACQUIRE, "agent");
;         asm volatile("s_waitcnt vmcnt(0)" ::: "memory");
;     }
;     __syncthreads();
; }
; __global__ void __launch_bounds__(512, 2) mega(Params p) {
;     ...
;     grid.sync();
.LBB0_95:
	v_lshrrev_b32_e32 v1, 20, v0
	v_lshrrev_b32_e32 v0, 10, v0
	v_or_b32_e32 v0, v0, v1
	s_movk_i32 s0, 0x3ff
	v_and_or_b32 v0, v0, s0, v210
	v_cmp_eq_u32_e32 vcc, 0, v0
	s_waitcnt vmcnt(0) lgkmcnt(0)
	s_barrier
	s_and_saveexec_b64 s[0:1], vcc
	s_cbranch_execz .LBB0_105
	buffer_wbl2 sc1
	s_waitcnt vmcnt(0)
	v_readlane_b32 s2, v254, 0
	v_readlane_b32 s3, v254, 1
	s_add_u32 s2, s2, 0x3a800000
	s_addc_u32 s3, s3, 0
	v_mov_b32_e32 v2, 0
	v_mov_b32_e32 v3, 1
	global_atomic_add v2, v3, s[2:3]
.Lcg_poll:
	global_load_dword v1, v2, s[2:3] sc1
	s_waitcnt vmcnt(0)
	v_cmp_le_u32_e32 vcc, s90, v1
	s_cbranch_vccnz .Lcg_done
	s_sleep 2
	s_branch .Lcg_poll

; __global__ void __launch_bounds__(512, 2) mega(Params p) {
;     ...
;     float* X = (float*)(p.ws + WS_X);
;     unsigned char* R1 = p.ws + WS_R1;
;     bf16_t* Y = (bf16_t*)(p.ws + WS_Y);
;     bf16_t* H = (bf16_t*)((unsigned char*)p.out + OB_H);
;     const bf16_t* Wb = (const bf16_t*)((unsigned char*)p.out + OB_W);
;     const float* MOD = (const float*)((unsigned char*)p.out + OB_MOD);
;     const f32x2* CS = (const f32x2*)((unsigned char*)p.out + OB_CS);
;     const TileMap idm = {1 << 30, 0, 0};
;     unsigned* bar = (unsigned*)(p.ws + WS_BAR); unsigned btarget = 0;
;     phase0(p, (float*)shm);
;     grid.sync();
;     for (int layer = 0; layer < 4; ++layer) {
;         const bool last = layer == 3;
;         const bool use_ret = (layer & 1) == 0;
;         const int lj = layer >> 1;
;         const float* modl = MOD + (size_t)layer * 33 * 6144;
;         const int r0 = last ? TCTX : 0;
;         const TileMap rowmap = last ? TileMap{0, 0, 32} : idm;
;         const int Mrows = last ? (TT - TCTX) : TT;
;         const bool latpost = layer >= 2;
;         const int r0p = latpost ? TCTX : 0;
;         const TileMap rowmapp = latpost ? TileMap{0, 0, 32} : idm;
;         const int Mrowsp = latpost ? (TT - TCTX) : TT;
;         const float* Xc = layer == 0 ? p.ctx : X; const float* Xl = layer == 0 ? p.x - (size_t)TCTX * 1024 : X;
;         const bool fuse_np = !use_ret && ((TT - r0) % ((int)gridDim.x * 4) == 0);
.LBB0_105:
	s_or_b64 exec, exec, s[0:1]
	v_readlane_b32 s16, v254, 0
	v_readlane_b32 s17, v254, 1
	s_add_u32 s34, s16, 0x12000000
	s_addc_u32 s35, s17, 0
	s_add_u32 s38, s16, 0x28800000
	s_addc_u32 s39, s17, 0
	v_readlane_b32 s0, v254, 6
	s_add_u32 s42, s16, 0x3a800000
	v_readlane_b32 s1, v254, 7
	s_addc_u32 s43, s17, 0
	s_mov_b64 s[80:81], s[0:1]
	s_add_u32 s0, s80, 0xfe000000
	v_readlane_b32 s2, v254, 8
	v_readlane_b32 s3, v254, 9
	v_readlane_b32 s4, v254, 10
	v_readlane_b32 s5, v254, 11
	v_readlane_b32 s6, v254, 12
	v_readlane_b32 s7, v254, 13
	v_readlane_b32 s8, v254, 14
	v_readlane_b32 s9, v254, 15
	v_readlane_b32 s10, v254, 16
	v_readlane_b32 s11, v254, 17
	v_readlane_b32 s12, v254, 18
	v_readlane_b32 s13, v254, 19
	v_readlane_b32 s14, v254, 20
	v_readlane_b32 s15, v254, 21
	v_writelane_b32 v254, s0, 24
	s_addc_u32 s0, s81, -1
	v_writelane_b32 v254, s0, 25
	s_lshl_b32 s0, s37, 3
	s_lshl_b32 s2, s90, 2
	s_lshl_b32 s74, s37, 5
	s_lshl_b32 s70, s90, 5
	v_writelane_b32 v254, s0, 26
	s_lshl_b32 s0, s90, 3
	v_writelane_b32 v254, s0, 27
	s_add_u32 s0, s22, 0xb000000
	v_writelane_b32 v254, s0, 28
	s_addc_u32 s0, s23, 0
	s_ashr_i32 s33, s37, 31
	v_writelane_b32 v254, s0, 29
	s_lshr_b32 s0, s33, 29
	s_add_i32 s0, s37, s0
	s_ashr_i32 s75, s0, 3
	s_and_b32 s0, s0, -8
	s_sub_i32 s80, s37, s0
	s_ashr_i32 s81, s90, 31
	s_cmp_lg_u64 s[62:63], 0
	s_cselect_b64 s[0:1], -1, 0
	s_add_u32 s40, s16, 0x16800000
	s_addc_u32 s41, s17, 0
	s_add_u32 s48, s16, 0x1b000000
	s_addc_u32 s49, s17, 0
	v_writelane_b32 v254, s0, 30
	s_cmpk_lt_i32 s37, 0x900
	s_movk_i32 s3, 0x121
	v_writelane_b32 v254, s1, 31
	s_cselect_b64 s[0:1], -1, 0
	v_writelane_b32 v254, s0, 32
	s_cmpk_lt_i32 s37, 0x100
	v_mov_b32_e32 v211, 0xc0
	v_writelane_b32 v254, s1, 33
	s_cselect_b64 s[0:1], -1, 0
	v_writelane_b32 v254, s0, 34
	v_bfrev_b32_e32 v212, 0.5
	v_mov_b32_e32 v213, 0x7ff
	v_writelane_b32 v254, s1, 35
	s_add_u32 s0, s16, 0x3a800100
	s_addc_u32 s1, s17, 0
	v_writelane_b32 v254, s0, 36
	v_mov_b32_e32 v214, 0xff
	v_mov_b32_e32 v215, 0x800
	v_writelane_b32 v254, s1, 37
	s_lshl_b32 s0, s37, 4
	v_writelane_b32 v254, s0, 38
	s_lshl_b32 s0, s90, 4
	v_writelane_b32 v254, s0, 39
	s_add_u32 s0, s22, 0xa800000
	v_writelane_b32 v254, s0, 40
	s_addc_u32 s0, s23, 0
	v_writelane_b32 v254, s0, 41
	s_add_u32 s0, s22, 0xb100000
	v_writelane_b32 v254, s0, 42
	s_addc_u32 s0, s23, 0
	v_writelane_b32 v254, s0, 43
	s_add_u32 s0, s22, 0xdd00000
	v_writelane_b32 v254, s0, 44
	s_addc_u32 s0, s23, 0
	s_cmp_lt_i32 s80, 0
	v_writelane_b32 v254, s0, 45
	s_cselect_b64 s[0:1], -1, 0
	v_writelane_b32 v254, s0, 46
	v_mov_b32_e32 v216, 0x100
	v_mov_b32_e32 v217, 0x7ffff800
	v_writelane_b32 v254, s1, 47
	s_and_b64 s[0:1], s[0:1], exec
	s_cselect_b32 s0, s3, 0x120
	s_mul_i32 s0, s80, s0
	s_add_i32 s0, s0, s75
	s_ashr_i32 s1, s0, 31
	s_lshr_b32 s1, s1, 26
	s_add_i32 s1, s0, s1
	s_ashr_i32 s3, s1, 6
	s_and_b32 s1, s1, 0xffc0
	s_sub_i32 s1, s0, s1
	s_bfe_i32 s0, s1, 0x80000
	s_bfe_u32 s0, s0, 0x2000d
	s_add_i32 s4, s1, s0
	s_bfe_i32 s0, s4, 0x80000
	s_and_b32 s4, s4, 0xfc
	s_sub_i32 s1, s1, s4
	s_lshl_b32 s3, s3, 2
	s_sext_i32_i16 s5, s0
	s_sext_i32_i8 s1, s1
	s_add_i32 s1, s3, s1
	s_ashr_i32 s3, s5, 2
	s_lshr_b32 s0, s5, 2
	v_writelane_b32 v254, s3, 48
	s_lshr_b32 s3, s80, 31
	s_cmp_lt_i32 s1, 16
	s_cselect_b64 s[4:5], -1, 0
	s_abs_i32 s2, s2
	v_cvt_f32_u32_e32 v0, s2
	v_writelane_b32 v254, s3, 49
	s_abs_i32 s3, s90
	v_cvt_f32_u32_e32 v1, s3
	v_rcp_iflag_f32_e32 v0, v0
	v_writelane_b32 v254, s1, 50
	v_writelane_b32 v254, s4, 51
	v_rcp_iflag_f32_e32 v1, v1
	v_mul_f32_e32 v0, 0x4f7ffffe, v0
	v_cvt_u32_f32_e32 v0, v0
	s_bfe_i64 s[0:1], s[0:1], 0x100000
	v_writelane_b32 v254, s5, 52
	s_lshl_b64 s[0:1], s[0:1], 19
	v_writelane_b32 v254, s0, 53
	v_mov_b32_e32 v218, 0xffffff00
	v_mov_b32_e32 v219, 1
	v_writelane_b32 v254, s1, 54
	v_readfirstlane_b32 s1, v0
	v_mul_f32_e32 v0, 0x4f7ffffe, v1
	s_sub_i32 s0, 0, s2
	v_cvt_u32_f32_e32 v0, v0
	s_mul_i32 s0, s0, s1
	s_mul_hi_u32 s0, s1, s0
	v_writelane_b32 v254, s2, 55
	s_add_i32 s0, s1, s0
	v_writelane_b32 v254, s0, 56
	s_sub_i32 s0, 0, s3
	v_readfirstlane_b32 s1, v0
	s_mul_i32 s0, s0, s1
	s_mul_hi_u32 s0, s1, s0
	v_writelane_b32 v254, s3, 57
	s_add_i32 s0, s1, s0
	v_writelane_b32 v254, s0, 58
	s_add_u32 s0, s22, 0x1e00
	s_addc_u32 s1, s23, 0
	v_writelane_b32 v254, s0, 59
	s_ashr_i32 s71, s70, 31
	s_lshl_b64 s[92:93], s[70:71], 11
	v_writelane_b32 v254, s1, 60
	s_lshl_b64 s[0:1], s[70:71], 12
	v_writelane_b32 v254, s0, 61
	v_mov_b32_e32 v0, 0
	v_mov_b32_e32 v220, 0xc0a00000
	v_writelane_b32 v254, s1, 62
	s_add_u32 s0, s22, 0x400
	s_addc_u32 s1, s23, 0
	v_writelane_b32 v254, s0, 63
	v_mov_b32_e32 v221, 0x40c00000
	v_mov_b32_e32 v222, 0xc0c00000
	v_writelane_b32 v255, s1, 0
	s_mov_b32 s0, 0x358637bd
	v_mov_b64_e32 v[178:179], s[0:1]
	v_cmp_eq_u32_e64 s[0:1], 0, v210
	v_mov_b32_e32 v223, 0x40e00000
	v_mov_b32_e32 v224, 0xc0e00000
	v_writelane_b32 v255, s0, 1
	s_movk_i32 s71, 0x2000
	s_movk_i32 s36, 0xf000
	v_writelane_b32 v255, s1, 2
	s_mov_b32 s0, s70
	v_writelane_b32 v255, s0, 3
	s_mov_b32 s45, 0x10000
	s_mov_b32 s46, 0x18000
	v_writelane_b32 v255, s1, 4
	v_writelane_b32 v255, s74, 5
	v_writelane_b32 v255, s75, 6
	v_writelane_b32 v255, s80, 7
	v_writelane_b32 v255, s92, 8
	s_mov_b32 s47, 0x8000
	s_movk_i32 s94, 0xa0
	v_writelane_b32 v255, s93, 9
	v_writelane_b32 v255, s20, 10
	s_mov_b32 s95, 0xbfb8aa3b
	s_movk_i32 s96, 0x210
	v_writelane_b32 v255, s21, 11
	v_writelane_b32 v255, s22, 12
	s_add_i32 s97, 0, 0x17800
	s_movk_i32 s98, 0x220
	s_movk_i32 s99, 0x110
	s_add_i32 s51, 0, 0x10c00
	s_mov_b32 s4, 0
	s_mov_b32 s88, s90
	s_mov_b32 s77, 0
	s_mov_b64 s[68:69], 0x1000
	s_mov_b64 s[82:83], 0x20000
	s_mov_b64 s[84:85], 0x10000
	s_mov_b64 s[86:87], 0x80
	v_writelane_b32 v255, s23, 13
	s_barrier
	s_branch .LBB0_108
